# residual-gate epilogue: counted vmcnt(15) waits per 8-element block instead of one vmcnt(0) for all 20 loads (wait moved to first consumer)
# speedup vs baseline: 1.0097x; 1.0097x over previous
; __device__ __forceinline__ unsigned cvt_pk_bf16(float lo, float hi) { unsigned r; asm volatile("v_cvt_pk_bf16_f32 %0, %1, %2" : "=v"(r) : "v"(lo), "v"(hi)); return r; }
;     __device__ __forceinline__ void operator()(const f32x4 (&acc)[2][2][4][2], const Unit& u, int wr, int wc, int fr, int fq) const {
;         const int row0 = u.pm * BM + wr * 64 + fr, col0 = u.pn * BM + wc * 32 + 8 * fq; const float* gp = gate + (size_t)(u.pm >> 3) * gstride + col0;
;         f32x4 gv[2][2];
; #pragma unroll
;         for (int bj = 0; bj < 2; ++bj)
; #pragma unroll
;             for (int n = 0; n < 2; ++n) gv[bj][n] = *(const f32x4*)(gp + bj * HALF + 4 * n);
; #pragma unroll
;         for (int ai = 0; ai < 2; ++ai)
; #pragma unroll
;             for (int m = 0; m < 4; ++m) { const size_t off = (size_t)(row0 + ai * HALF + m * 16) * ldc + col0;
; #pragma unroll
;                 for (int bj = 0; bj < 2; ++bj) { const u32x4 bw = *(const u32x4*)(base + off + bj * HALF);
;                     const f32x4 a0 = acc[ai][bj][m][0], a1 = acc[ai][bj][m][1], g0 = gv[bj][0], g1 = gv[bj][1];
;                     u32x4 w;
;                     w.x = cvt_pk_bf16(__uint_as_float(bw.x << 16) + g0[0] * a0[0], __uint_as_float(bw.x & 0xffff0000u) + g0[1] * a0[1]);
;                     w.y = cvt_pk_bf16(__uint_as_float(bw.y << 16) + g0[2] * a0[2], __uint_as_float(bw.y & 0xffff0000u) + g0[3] * a0[3]);
;                     w.z = cvt_pk_bf16(__uint_as_float(bw.z << 16) + g1[0] * a1[0], __uint_as_float(bw.z & 0xffff0000u) + g1[1] * a1[1]);
;                     w.w = cvt_pk_bf16(__uint_as_float(bw.w << 16) + g1[2] * a1[2], __uint_as_float(bw.w & 0xffff0000u) + g1[3] * a1[3]);
;                     *(u32x4*)(out + off + bj * HALF) = w; } }
;     }
.LBB0_182:
	v_lshl_add_u32 v162, s45, 8, v1
	v_lshl_or_b32 v160, s46, 8, v168
	v_ashrrev_i32_e32 v163, 31, v162
	v_ashrrev_i32_e32 v161, 31, v160
	v_lshlrev_b64 v[106:107], 11, v[162:163]
	v_lshl_add_u64 v[106:107], v[106:107], 0, v[160:161]
	v_lshlrev_b64 v[158:159], 1, v[106:107]
	s_ashr_i32 s24, s45, 3
	v_lshl_add_u64 v[174:175], s[10:11], 0, v[158:159]
	s_mul_hi_i32 s25, s24, 0xc000
	s_mul_i32 s24, s24, 0xc000
	global_load_dwordx4 v[170:173], v[174:175], off
	s_add_u32 s24, s37, s24
	s_addc_u32 s25, s38, s25
	v_lshl_add_u64 v[110:111], v[160:161], 2, s[24:25]
	global_load_dwordx4 v[134:137], v[110:111], off
	global_load_dwordx4 v[130:133], v[110:111], off offset:16
	global_load_dwordx4 v[106:109], v[110:111], off offset:528
	s_nop 0
	global_load_dwordx4 v[110:113], v[110:111], off offset:512
	global_load_dwordx4 v[182:185], v[174:175], off offset:256
	s_mov_b64 s[24:25], 0x10000
	v_lshl_add_u64 v[218:219], v[174:175], 0, s[24:25]
	global_load_dwordx4 v[186:189], v[218:219], off
	global_load_dwordx4 v[190:193], v[218:219], off offset:256
	s_mov_b64 s[24:25], 0x20000
	v_lshl_add_u64 v[218:219], v[174:175], 0, s[24:25]
	global_load_dwordx4 v[194:197], v[218:219], off
	global_load_dwordx4 v[198:201], v[218:219], off offset:256
	s_mov_b64 s[24:25], 0x30000
	v_lshl_add_u64 v[218:219], v[174:175], 0, s[24:25]
	global_load_dwordx4 v[202:205], v[218:219], off
	global_load_dwordx4 v[206:209], v[218:219], off offset:256
	s_mov_b64 s[24:25], 0x80000
	v_lshl_add_u64 v[218:219], v[174:175], 0, s[24:25]
	global_load_dwordx4 v[210:213], v[218:219], off
	global_load_dwordx4 v[226:229], v[218:219], off offset:256
	s_mov_b64 s[24:25], 0x90000
	v_lshl_add_u64 v[218:219], v[174:175], 0, s[24:25]
	global_load_dwordx4 v[230:233], v[218:219], off
	global_load_dwordx4 v[234:237], v[218:219], off offset:256
	s_mov_b64 s[24:25], 0xa0000
	v_lshl_add_u64 v[218:219], v[174:175], 0, s[24:25]
	global_load_dwordx4 v[238:241], v[218:219], off
	global_load_dwordx4 v[242:245], v[218:219], off offset:256
	s_mov_b64 s[24:25], 0xb0000
	v_lshl_add_u64 v[218:219], v[174:175], 0, s[24:25]
	global_load_dwordx4 v[246:249], v[218:219], off
	global_load_dwordx4 v[250:253], v[218:219], off offset:256
	v_lshl_add_u64 v[176:177], s[16:17], 0, v[158:159]
	s_mov_b64 s[24:25], 0x80000
	s_and_b64 vcc, exec, s[6:7]
	s_mov_b64 s[6:7], -1
	s_waitcnt vmcnt(15)
	v_lshlrev_b32_e32 v163, 16, v170
	v_and_b32_e32 v170, 0xffff0000, v170
	v_lshlrev_b32_e32 v178, 16, v171
	v_and_b32_e32 v171, 0xffff0000, v171
	v_lshlrev_b32_e32 v179, 16, v172
	v_and_b32_e32 v172, 0xffff0000, v172
	v_lshlrev_b32_e32 v180, 16, v173
	v_and_b32_e32 v173, 0xffff0000, v173
	v_fmac_f32_e32 v163, v142, v134
	v_fmac_f32_e32 v170, v143, v135
	v_fmac_f32_e32 v178, v144, v136
	v_fmac_f32_e32 v171, v145, v137
	v_fmac_f32_e32 v179, v138, v130
	v_fmac_f32_e32 v172, v139, v131
	v_fmac_f32_e32 v180, v140, v132
	v_fmac_f32_e32 v173, v141, v133
	v_cvt_pk_bf16_f32 v138, v163, v170
	v_cvt_pk_bf16_f32 v139, v178, v171
	v_cvt_pk_bf16_f32 v140, v179, v172
	v_cvt_pk_bf16_f32 v141, v180, v173
	global_store_dwordx4 v[176:177], v[138:141], off
	v_or_b32_e32 v142, 16, v162
	v_ashrrev_i32_e32 v143, 31, v142
	v_lshlrev_b64 v[142:143], 11, v[142:143]
	v_lshl_add_u64 v[142:143], v[142:143], 0, v[160:161]
	v_lshlrev_b64 v[142:143], 1, v[142:143]
	v_lshl_add_u64 v[144:145], s[10:11], 0, v[142:143]
	s_waitcnt vmcnt(15)
	v_lshlrev_b32_e32 v163, 16, v182
	v_and_b32_e32 v138, 0xffff0000, v182
	v_lshlrev_b32_e32 v170, 16, v183
	v_and_b32_e32 v139, 0xffff0000, v183
	v_lshlrev_b32_e32 v171, 16, v184
	v_and_b32_e32 v140, 0xffff0000, v184
	v_lshlrev_b32_e32 v172, 16, v185
	v_and_b32_e32 v141, 0xffff0000, v185
	v_fmac_f32_e32 v163, v126, v110
	v_fmac_f32_e32 v138, v127, v111
	v_fmac_f32_e32 v170, v128, v112
	v_fmac_f32_e32 v139, v129, v113
	v_fmac_f32_e32 v171, v122, v106
	v_fmac_f32_e32 v140, v123, v107
	v_fmac_f32_e32 v172, v124, v108
	v_fmac_f32_e32 v141, v125, v109
	v_cvt_pk_bf16_f32 v122, v163, v138
	v_cvt_pk_bf16_f32 v123, v170, v139
	v_cvt_pk_bf16_f32 v124, v171, v140
	v_cvt_pk_bf16_f32 v125, v172, v141
	global_store_dwordx4 v[176:177], v[122:125], off offset:256
	v_lshl_add_u64 v[126:127], s[16:17], 0, v[142:143]
	s_waitcnt vmcnt(15)
	v_lshlrev_b32_e32 v128, 16, v186
	v_and_b32_e32 v122, 0xffff0000, v186
	v_lshlrev_b32_e32 v129, 16, v187
	v_and_b32_e32 v123, 0xffff0000, v187
	v_lshlrev_b32_e32 v138, 16, v188
	v_and_b32_e32 v124, 0xffff0000, v188
	v_lshlrev_b32_e32 v139, 16, v189
	v_and_b32_e32 v125, 0xffff0000, v189
	v_fmac_f32_e32 v128, v118, v134
	v_fmac_f32_e32 v122, v119, v135
	v_fmac_f32_e32 v129, v120, v136
	v_fmac_f32_e32 v123, v121, v137
	v_fmac_f32_e32 v138, v114, v130
	v_fmac_f32_e32 v124, v115, v131
	v_fmac_f32_e32 v139, v116, v132
	v_fmac_f32_e32 v125, v117, v133
	v_cvt_pk_bf16_f32 v114, v128, v122
	v_cvt_pk_bf16_f32 v115, v129, v123
	v_cvt_pk_bf16_f32 v116, v138, v124
	v_cvt_pk_bf16_f32 v117, v139, v125
	global_store_dwordx4 v[126:127], v[114:117], off
	v_or_b32_e32 v118, 32, v162
	v_ashrrev_i32_e32 v119, 31, v118
	v_lshlrev_b64 v[118:119], 11, v[118:119]
	v_lshl_add_u64 v[118:119], v[118:119], 0, v[160:161]
	v_lshlrev_b64 v[118:119], 1, v[118:119]
	v_lshl_add_u64 v[120:121], s[10:11], 0, v[118:119]
	s_waitcnt vmcnt(15)
	v_lshlrev_b32_e32 v122, 16, v190
	v_and_b32_e32 v114, 0xffff0000, v190
	v_lshlrev_b32_e32 v123, 16, v191
	v_and_b32_e32 v115, 0xffff0000, v191
	v_lshlrev_b32_e32 v124, 16, v192
	v_and_b32_e32 v116, 0xffff0000, v192
	v_lshlrev_b32_e32 v125, 16, v193
	v_and_b32_e32 v117, 0xffff0000, v193
	v_fmac_f32_e32 v122, v102, v110
	v_fmac_f32_e32 v114, v103, v111
	v_fmac_f32_e32 v123, v104, v112
	v_fmac_f32_e32 v115, v105, v113
	v_fmac_f32_e32 v124, v98, v106
	v_fmac_f32_e32 v116, v99, v107
	v_fmac_f32_e32 v125, v100, v108
	v_fmac_f32_e32 v117, v101, v109
	v_cvt_pk_bf16_f32 v98, v122, v114
	v_cvt_pk_bf16_f32 v99, v123, v115
	v_cvt_pk_bf16_f32 v100, v124, v116
	v_cvt_pk_bf16_f32 v101, v125, v117
	global_store_dwordx4 v[126:127], v[98:101], off offset:256
	v_lshl_add_u64 v[102:103], s[16:17], 0, v[118:119]
	s_waitcnt vmcnt(15)
; __device__ __forceinline__ unsigned cvt_pk_bf16(float lo, float hi) { unsigned r; asm volatile("v_cvt_pk_bf16_f32 %0, %1, %2" : "=v"(r) : "v"(lo), "v"(hi)); return r; }
;     __device__ __forceinline__ void operator()(const f32x4 (&acc)[2][2][4][2], const Unit& u, int wr, int wc, int fr, int fq) const {
;     ...
;             for (int m = 0; m < 4; ++m) { const size_t off = (size_t)(row0 + ai * HALF + m * 16) * ldc + col0;
; #pragma unroll
;                 for (int bj = 0; bj < 2; ++bj) { const u32x4 bw = *(const u32x4*)(base + off + bj * HALF);
;                     const f32x4 a0 = acc[ai][bj][m][0], a1 = acc[ai][bj][m][1], g0 = gv[bj][0], g1 = gv[bj][1];
;                     u32x4 w;
;                     w.x = cvt_pk_bf16(__uint_as_float(bw.x << 16) + g0[0] * a0[0], __uint_as_float(bw.x & 0xffff0000u) + g0[1] * a0[1]);
;                     w.y = cvt_pk_bf16(__uint_as_float(bw.y << 16) + g0[2] * a0[2], __uint_as_float(bw.y & 0xffff0000u) + g0[3] * a0[3]);
;                     w.z = cvt_pk_bf16(__uint_as_float(bw.z << 16) + g1[0] * a1[0], __uint_as_float(bw.z & 0xffff0000u) + g1[1] * a1[1]);
;                     w.w = cvt_pk_bf16(__uint_as_float(bw.w << 16) + g1[2] * a1[2], __uint_as_float(bw.w & 0xffff0000u) + g1[3] * a1[3]);
;                     *(u32x4*)(out + off + bj * HALF) = w; } }
	v_lshlrev_b32_e32 v104, 16, v194
	v_and_b32_e32 v98, 0xffff0000, v194
	v_lshlrev_b32_e32 v105, 16, v195
	v_and_b32_e32 v99, 0xffff0000, v195
	v_lshlrev_b32_e32 v114, 16, v196
	v_and_b32_e32 v100, 0xffff0000, v196
	v_lshlrev_b32_e32 v115, 16, v197
	v_and_b32_e32 v101, 0xffff0000, v197
	v_fmac_f32_e32 v104, v94, v134
	v_fmac_f32_e32 v98, v95, v135
	v_fmac_f32_e32 v105, v96, v136
	v_fmac_f32_e32 v99, v97, v137
	v_fmac_f32_e32 v114, v90, v130
	v_fmac_f32_e32 v100, v91, v131
	v_fmac_f32_e32 v115, v92, v132
	v_fmac_f32_e32 v101, v93, v133
	v_cvt_pk_bf16_f32 v90, v104, v98
	v_cvt_pk_bf16_f32 v91, v105, v99
	v_cvt_pk_bf16_f32 v92, v114, v100
	v_cvt_pk_bf16_f32 v93, v115, v101
	global_store_dwordx4 v[102:103], v[90:93], off
	v_or_b32_e32 v94, 48, v162
	v_ashrrev_i32_e32 v95, 31, v94
	v_lshlrev_b64 v[94:95], 11, v[94:95]
	v_lshl_add_u64 v[94:95], v[94:95], 0, v[160:161]
	v_lshlrev_b64 v[94:95], 1, v[94:95]
	v_lshl_add_u64 v[96:97], s[10:11], 0, v[94:95]
	s_waitcnt vmcnt(15)
	v_lshlrev_b32_e32 v98, 16, v198
	v_and_b32_e32 v90, 0xffff0000, v198
	v_lshlrev_b32_e32 v99, 16, v199
	v_and_b32_e32 v91, 0xffff0000, v199
	v_lshlrev_b32_e32 v100, 16, v200
	v_and_b32_e32 v92, 0xffff0000, v200
	v_lshlrev_b32_e32 v101, 16, v201
	v_and_b32_e32 v93, 0xffff0000, v201
	v_fmac_f32_e32 v98, v86, v110
	v_fmac_f32_e32 v90, v87, v111
	v_fmac_f32_e32 v99, v88, v112
	v_fmac_f32_e32 v91, v89, v113
	v_fmac_f32_e32 v100, v82, v106
	v_fmac_f32_e32 v92, v83, v107
	v_fmac_f32_e32 v101, v84, v108
	v_fmac_f32_e32 v93, v85, v109
	v_cvt_pk_bf16_f32 v82, v98, v90
	v_cvt_pk_bf16_f32 v83, v99, v91
	v_cvt_pk_bf16_f32 v84, v100, v92
	v_cvt_pk_bf16_f32 v85, v101, v93
	global_store_dwordx4 v[102:103], v[82:85], off offset:256
	v_lshl_add_u64 v[86:87], s[16:17], 0, v[94:95]
	s_waitcnt vmcnt(15)
	v_lshlrev_b32_e32 v88, 16, v202
	v_and_b32_e32 v82, 0xffff0000, v202
	v_lshlrev_b32_e32 v89, 16, v203
	v_and_b32_e32 v83, 0xffff0000, v203
	v_lshlrev_b32_e32 v90, 16, v204
	v_and_b32_e32 v84, 0xffff0000, v204
	v_lshlrev_b32_e32 v91, 16, v205
	v_and_b32_e32 v85, 0xffff0000, v205
	v_fmac_f32_e32 v88, v78, v134
	v_fmac_f32_e32 v82, v79, v135
	v_fmac_f32_e32 v89, v80, v136
	v_fmac_f32_e32 v83, v81, v137
	v_fmac_f32_e32 v90, v74, v130
	v_fmac_f32_e32 v84, v75, v131
	v_fmac_f32_e32 v91, v76, v132
	v_fmac_f32_e32 v85, v77, v133
	v_cvt_pk_bf16_f32 v74, v88, v82
	v_cvt_pk_bf16_f32 v75, v89, v83
	v_cvt_pk_bf16_f32 v76, v90, v84
	v_cvt_pk_bf16_f32 v77, v91, v85
	global_store_dwordx4 v[86:87], v[74:77], off
	v_lshl_add_u64 v[78:79], v[158:159], 0, s[24:25]
	v_lshl_add_u64 v[80:81], s[10:11], 0, v[78:79]
	s_mov_b64 s[24:25], 0x90000
	s_waitcnt vmcnt(15)
	v_lshlrev_b32_e32 v82, 16, v206
	v_and_b32_e32 v74, 0xffff0000, v206
	v_lshlrev_b32_e32 v83, 16, v207
	v_and_b32_e32 v75, 0xffff0000, v207
	v_lshlrev_b32_e32 v84, 16, v208
	v_and_b32_e32 v76, 0xffff0000, v208
	v_lshlrev_b32_e32 v85, 16, v209
	v_and_b32_e32 v77, 0xffff0000, v209
	v_fmac_f32_e32 v82, v70, v110
	v_fmac_f32_e32 v74, v71, v111
	v_fmac_f32_e32 v83, v72, v112
	v_fmac_f32_e32 v75, v73, v113
	v_fmac_f32_e32 v84, v66, v106
	v_fmac_f32_e32 v76, v67, v107
	v_fmac_f32_e32 v85, v68, v108
	v_fmac_f32_e32 v77, v69, v109
	v_cvt_pk_bf16_f32 v66, v82, v74
	v_cvt_pk_bf16_f32 v67, v83, v75
	v_cvt_pk_bf16_f32 v68, v84, v76
	v_cvt_pk_bf16_f32 v69, v85, v77
	global_store_dwordx4 v[86:87], v[66:69], off offset:256
	v_lshl_add_u64 v[70:71], s[16:17], 0, v[78:79]
	s_waitcnt vmcnt(15)
	v_lshlrev_b32_e32 v72, 16, v210
	v_and_b32_e32 v66, 0xffff0000, v210
	v_lshlrev_b32_e32 v73, 16, v211
	v_and_b32_e32 v67, 0xffff0000, v211
	v_lshlrev_b32_e32 v74, 16, v212
	v_and_b32_e32 v68, 0xffff0000, v212
	v_lshlrev_b32_e32 v75, 16, v213
	v_and_b32_e32 v69, 0xffff0000, v213
	v_fmac_f32_e32 v72, v62, v134
	v_fmac_f32_e32 v66, v63, v135
	v_fmac_f32_e32 v73, v64, v136
	v_fmac_f32_e32 v67, v65, v137
	v_fmac_f32_e32 v74, v58, v130
	v_fmac_f32_e32 v68, v59, v131
	v_fmac_f32_e32 v75, v60, v132
	v_fmac_f32_e32 v69, v61, v133
	v_cvt_pk_bf16_f32 v58, v72, v66
	v_cvt_pk_bf16_f32 v59, v73, v67
	v_cvt_pk_bf16_f32 v60, v74, v68
	v_cvt_pk_bf16_f32 v61, v75, v69
	global_store_dwordx4 v[70:71], v[58:61], off
	v_lshl_add_u64 v[62:63], v[158:159], 0, s[24:25]
	v_lshl_add_u64 v[64:65], s[10:11], 0, v[62:63]
	s_mov_b64 s[24:25], 0xa0000
	s_waitcnt vmcnt(15)
	v_lshlrev_b32_e32 v66, 16, v226
	v_and_b32_e32 v58, 0xffff0000, v226
	v_lshlrev_b32_e32 v67, 16, v227
	v_and_b32_e32 v59, 0xffff0000, v227
	v_lshlrev_b32_e32 v68, 16, v228
	v_and_b32_e32 v60, 0xffff0000, v228
	v_lshlrev_b32_e32 v69, 16, v229
	v_and_b32_e32 v61, 0xffff0000, v229
	v_fmac_f32_e32 v66, v54, v110
	v_fmac_f32_e32 v58, v55, v111
	v_fmac_f32_e32 v67, v56, v112
	v_fmac_f32_e32 v59, v57, v113
	v_fmac_f32_e32 v68, v50, v106
	v_fmac_f32_e32 v60, v51, v107
	v_fmac_f32_e32 v69, v52, v108
	v_fmac_f32_e32 v61, v53, v109
	v_cvt_pk_bf16_f32 v50, v66, v58
	v_cvt_pk_bf16_f32 v51, v67, v59
	v_cvt_pk_bf16_f32 v52, v68, v60
	v_cvt_pk_bf16_f32 v53, v69, v61
	global_store_dwordx4 v[70:71], v[50:53], off offset:256
	v_lshl_add_u64 v[54:55], s[16:17], 0, v[62:63]
	s_waitcnt vmcnt(15)
; __device__ __forceinline__ unsigned cvt_pk_bf16(float lo, float hi) { unsigned r; asm volatile("v_cvt_pk_bf16_f32 %0, %1, %2" : "=v"(r) : "v"(lo), "v"(hi)); return r; }
; #define PG8_BAR __builtin_amdgcn_s_barrier()
; template <class Epi, class Sched, bool ALIGN_EPI = false, bool SP2 = false>
; __device__ __forceinline__ void gemm_phase(PG8_LAS unsigned char* lds, const Gemm g, const Sched& S, const Epi& E) {
;     ...
;         if (!has_next) break;
; #pragma unroll
;         for (int a = 0; a < 2; ++a)
; #pragma unroll
;             for (int b = 0; b < 2; ++b)
; #pragma unroll
;                 for (int m = 0; m < 4; ++m)
; #pragma unroll
;                     for (int n = 0; n < 2; ++n) acc[a][b][m][n] = (f32x4){0.f, 0.f, 0.f, 0.f};
;         cur = nxt; cA = nA; cB = nB; ++ui;
;         if constexpr (ALIGN_EPI) { if (wr == 1) PG8_BAR; }
;     __device__ __forceinline__ void operator()(const f32x4 (&acc)[2][2][4][2], const Unit& u, int wr, int wc, int fr, int fq) const {
;     ...
;             for (int m = 0; m < 4; ++m) { const size_t off = (size_t)(row0 + ai * HALF + m * 16) * ldc + col0;
; #pragma unroll
;                 for (int bj = 0; bj < 2; ++bj) { const u32x4 bw = *(const u32x4*)(base + off + bj * HALF);
;                     const f32x4 a0 = acc[ai][bj][m][0], a1 = acc[ai][bj][m][1], g0 = gv[bj][0], g1 = gv[bj][1];
;                     u32x4 w;
;                     w.x = cvt_pk_bf16(__uint_as_float(bw.x << 16) + g0[0] * a0[0], __uint_as_float(bw.x & 0xffff0000u) + g0[1] * a0[1]);
;                     w.y = cvt_pk_bf16(__uint_as_float(bw.y << 16) + g0[2] * a0[2], __uint_as_float(bw.y & 0xffff0000u) + g0[3] * a0[3]);
;                     w.z = cvt_pk_bf16(__uint_as_float(bw.z << 16) + g1[0] * a1[0], __uint_as_float(bw.z & 0xffff0000u) + g1[1] * a1[1]);
;                     w.w = cvt_pk_bf16(__uint_as_float(bw.w << 16) + g1[2] * a1[2], __uint_as_float(bw.w & 0xffff0000u) + g1[3] * a1[3]);
;                     *(u32x4*)(out + off + bj * HALF) = w; } }
	v_lshlrev_b32_e32 v56, 16, v230
	v_and_b32_e32 v50, 0xffff0000, v230
	v_lshlrev_b32_e32 v57, 16, v231
	v_and_b32_e32 v51, 0xffff0000, v231
	v_lshlrev_b32_e32 v58, 16, v232
	v_and_b32_e32 v52, 0xffff0000, v232
	v_lshlrev_b32_e32 v59, 16, v233
	v_and_b32_e32 v53, 0xffff0000, v233
	v_fmac_f32_e32 v56, v46, v134
	v_fmac_f32_e32 v50, v47, v135
	v_fmac_f32_e32 v57, v48, v136
	v_fmac_f32_e32 v51, v49, v137
	v_fmac_f32_e32 v58, v42, v130
	v_fmac_f32_e32 v52, v43, v131
	v_fmac_f32_e32 v59, v44, v132
	v_fmac_f32_e32 v53, v45, v133
	v_cvt_pk_bf16_f32 v42, v56, v50
	v_cvt_pk_bf16_f32 v43, v57, v51
	v_cvt_pk_bf16_f32 v44, v58, v52
	v_cvt_pk_bf16_f32 v45, v59, v53
	global_store_dwordx4 v[54:55], v[42:45], off
	v_lshl_add_u64 v[46:47], v[158:159], 0, s[24:25]
	v_lshl_add_u64 v[48:49], s[10:11], 0, v[46:47]
	s_mov_b64 s[24:25], 0xb0000
	s_waitcnt vmcnt(15)
	v_lshlrev_b32_e32 v50, 16, v234
	v_and_b32_e32 v42, 0xffff0000, v234
	v_lshlrev_b32_e32 v51, 16, v235
	v_and_b32_e32 v43, 0xffff0000, v235
	v_lshlrev_b32_e32 v52, 16, v236
	v_and_b32_e32 v44, 0xffff0000, v236
	v_lshlrev_b32_e32 v53, 16, v237
	v_and_b32_e32 v45, 0xffff0000, v237
	v_fmac_f32_e32 v50, v38, v110
	v_fmac_f32_e32 v42, v39, v111
	v_fmac_f32_e32 v51, v40, v112
	v_fmac_f32_e32 v43, v41, v113
	v_fmac_f32_e32 v52, v34, v106
	v_fmac_f32_e32 v44, v35, v107
	v_fmac_f32_e32 v53, v36, v108
	v_fmac_f32_e32 v45, v37, v109
	v_cvt_pk_bf16_f32 v34, v50, v42
	v_cvt_pk_bf16_f32 v35, v51, v43
	v_cvt_pk_bf16_f32 v36, v52, v44
	v_cvt_pk_bf16_f32 v37, v53, v45
	global_store_dwordx4 v[54:55], v[34:37], off offset:256
	v_lshl_add_u64 v[38:39], s[16:17], 0, v[46:47]
	s_waitcnt vmcnt(15)
	v_lshlrev_b32_e32 v40, 16, v238
	v_and_b32_e32 v34, 0xffff0000, v238
	v_lshlrev_b32_e32 v41, 16, v239
	v_and_b32_e32 v35, 0xffff0000, v239
	v_lshlrev_b32_e32 v42, 16, v240
	v_and_b32_e32 v36, 0xffff0000, v240
	v_lshlrev_b32_e32 v43, 16, v241
	v_and_b32_e32 v37, 0xffff0000, v241
	v_fmac_f32_e32 v40, v30, v134
	v_fmac_f32_e32 v34, v31, v135
	v_fmac_f32_e32 v41, v32, v136
	v_fmac_f32_e32 v35, v33, v137
	v_fmac_f32_e32 v42, v26, v130
	v_fmac_f32_e32 v36, v27, v131
	v_fmac_f32_e32 v43, v28, v132
	v_fmac_f32_e32 v37, v29, v133
	v_cvt_pk_bf16_f32 v26, v40, v34
	v_cvt_pk_bf16_f32 v27, v41, v35
	v_cvt_pk_bf16_f32 v28, v42, v36
	v_cvt_pk_bf16_f32 v29, v43, v37
	global_store_dwordx4 v[38:39], v[26:29], off
	v_lshl_add_u64 v[30:31], v[158:159], 0, s[24:25]
	v_lshl_add_u64 v[32:33], s[10:11], 0, v[30:31]
	s_waitcnt vmcnt(15)
	v_lshlrev_b32_e32 v34, 16, v242
	v_and_b32_e32 v26, 0xffff0000, v242
	v_lshlrev_b32_e32 v35, 16, v243
	v_and_b32_e32 v27, 0xffff0000, v243
	v_lshlrev_b32_e32 v36, 16, v244
	v_and_b32_e32 v28, 0xffff0000, v244
	v_lshlrev_b32_e32 v37, 16, v245
	v_and_b32_e32 v29, 0xffff0000, v245
	v_fmac_f32_e32 v34, v22, v110
	v_fmac_f32_e32 v26, v23, v111
	v_fmac_f32_e32 v35, v24, v112
	v_fmac_f32_e32 v27, v25, v113
	v_fmac_f32_e32 v36, v18, v106
	v_fmac_f32_e32 v28, v19, v107
	v_fmac_f32_e32 v37, v20, v108
	v_fmac_f32_e32 v29, v21, v109
	v_cvt_pk_bf16_f32 v18, v34, v26
	v_cvt_pk_bf16_f32 v19, v35, v27
	v_cvt_pk_bf16_f32 v20, v36, v28
	v_cvt_pk_bf16_f32 v21, v37, v29
	global_store_dwordx4 v[38:39], v[18:21], off offset:256
	v_lshl_add_u64 v[22:23], s[16:17], 0, v[30:31]
	s_waitcnt vmcnt(15)
	v_lshlrev_b32_e32 v24, 16, v246
	v_and_b32_e32 v18, 0xffff0000, v246
	v_lshlrev_b32_e32 v25, 16, v247
	v_and_b32_e32 v19, 0xffff0000, v247
	v_lshlrev_b32_e32 v26, 16, v248
	v_and_b32_e32 v20, 0xffff0000, v248
	v_lshlrev_b32_e32 v27, 16, v249
	v_and_b32_e32 v21, 0xffff0000, v249
	v_fmac_f32_e32 v24, v14, v134
	v_fmac_f32_e32 v18, v15, v135
	v_fmac_f32_e32 v25, v16, v136
	v_fmac_f32_e32 v19, v17, v137
	v_fmac_f32_e32 v26, v10, v130
	v_fmac_f32_e32 v20, v11, v131
	v_fmac_f32_e32 v27, v12, v132
	v_fmac_f32_e32 v21, v13, v133
	v_cvt_pk_bf16_f32 v10, v24, v18
	v_cvt_pk_bf16_f32 v11, v25, v19
	v_cvt_pk_bf16_f32 v12, v26, v20
	v_cvt_pk_bf16_f32 v13, v27, v21
	global_store_dwordx4 v[22:23], v[10:13], off
	s_waitcnt vmcnt(15)
	v_lshlrev_b32_e32 v14, 16, v250
	v_and_b32_e32 v10, 0xffff0000, v250
	v_lshlrev_b32_e32 v15, 16, v251
	v_and_b32_e32 v11, 0xffff0000, v251
	v_lshlrev_b32_e32 v16, 16, v252
	v_and_b32_e32 v12, 0xffff0000, v252
	v_lshlrev_b32_e32 v17, 16, v253
	v_and_b32_e32 v13, 0xffff0000, v253
	v_fmac_f32_e32 v14, v6, v110
	v_fmac_f32_e32 v10, v7, v111
	v_fmac_f32_e32 v15, v8, v112
	v_fmac_f32_e32 v11, v9, v113
	v_fmac_f32_e32 v16, v2, v106
	v_fmac_f32_e32 v12, v3, v107
	v_fmac_f32_e32 v17, v4, v108
	v_fmac_f32_e32 v13, v5, v109
	v_cvt_pk_bf16_f32 v2, v14, v10
	v_cvt_pk_bf16_f32 v3, v15, v11
	v_cvt_pk_bf16_f32 v4, v16, v12
	v_cvt_pk_bf16_f32 v5, v17, v13
	global_store_dwordx4 v[22:23], v[2:5], off offset:256
	s_cbranch_vccnz .LBB0_167
	s_andn2_b64 vcc, exec, s[18:19]
	s_cbranch_vccnz .LBB0_166
	s_barrier
	s_branch .LBB0_166
